# G2 gated merge keeps running sum in accumulators (rescale by g_s/g_s+1 between K segments) - no f32 merged round trip
# speedup vs baseline: 1.0221x; 1.0221x over previous
; __device__ __forceinline__ u32x2 pack4(f32x4 v) { u32x2 r; r[0] = cvt_pk(v[0], v[1]); r[1] = cvt_pk(v[2], v[3]); return r; }
; __device__ __forceinline__ void epilogue(const Params& p, const Unit& u, const f32x4 (&acc)[2][2][4][2], int wr, int wc, int fr, int fq) {
;     ...
;   } else if (kind >= 9 && kind <= 11) {
;     const int seg = kind - 9;
;     const bf16_t* gates = (const bf16_t*)(ws + WS_GATES);
;     float* mf = (float*)(ws + WS_MERGED);
;     bf16_t* mb = (bf16_t*)(ws + WS_MERGEDB);
;     const int cb = u.pn * 256 + ct0;
; #pragma unroll
;     for (int ai = 0; ai < 2; ++ai)
; #pragma unroll
;       for (int mp = 0; mp < 2; ++mp) {
;         u32x2 gr[2][2][2]; f32x4 mv[2][2][2];
; #pragma unroll
;         for (int mm = 0; mm < 2; ++mm)
; #pragma unroll
;           for (int bj = 0; bj < 2; ++bj)
; #pragma unroll
;             for (int n = 0; n < 2; ++n) {
;               const size_t row = (size_t)(row0 + ai * 128 + (mp * 2 + mm) * 16);
;               const int col = cb + bj * 128 + n * 16;
;               gr[mm][bj][n] = *(const u32x2*)(gates + row * 6144 + seg * 2048 + col);
;               if (seg > 0) mv[mm][bj][n] = *(const f32x4*)(mf + row * 2048 + col);
;             }
; #pragma unroll
;         for (int mm = 0; mm < 2; ++mm)
; #pragma unroll
;           for (int bj = 0; bj < 2; ++bj)
; #pragma unroll
;             for (int n = 0; n < 2; ++n) {
;               const size_t row = (size_t)(row0 + ai * 128 + (mp * 2 + mm) * 16);
;               const int col = cb + bj * 128 + n * 16;
;               f32x4 v = acc[ai][bj][mp * 2 + mm][n] * unpack4(gr[mm][bj][n]);
;               if (seg > 0) v += mv[mm][bj][n];
;               if (seg < 2) *(f32x4*)(mf + row * 2048 + col) = v;
;               else *(u32x2*)(mb + row * 2048 + col) = pack4(v);
;             }
;       }
; __device__ __forceinline__ void gemm_phase(const Params& p, LAS unsigned char* lds, int gph, unsigned ldB  ) {
;     ...
;     epilogue(p, cur, acc, wr, wc, fr, fq);
;     if (!has_next) break;
; #pragma unroll
;     for (int a = 0; a < 2; ++a)
; #pragma unroll
;       for (int b = 0; b < 2; ++b)
; #pragma unroll
;         for (int m = 0; m < 4; ++m)
; #pragma unroll
;           for (int n = 0; n < 2; ++n) acc[a][b][m][n] = (f32x4){0.f, 0.f, 0.f, 0.f};
;     cur = nxt; cA = nA; cB = nB; ++ui;
.LBB0_786:
	s_mov_b64 s[36:37], 0
.LBB0_787:
	s_branch .LBB0_980
.Lgm_ep:
	s_lshl_b32 s30, s76, 12
	s_add_u32 s34, s24, s30
	s_addc_u32 s35, s25, 0
	s_add_u32 s34, s34, 0xc700000
	s_addc_u32 s35, s35, 0
	s_add_u32 s36, s34, 0x1000
	s_addc_u32 s37, s35, 0
	v_lshl_or_b32 v64, s78, 8, v174
	v_mul_u32_u24_e32 v67, 0x3000, v66
	v_lshl_add_u32 v64, v64, 1, v67
	s_mov_b32 s30, 0xffff0000
	s_mov_b32 s31, 0x0da24260
	s_cmp_eq_u32 s29, 2
	s_cbranch_scc1 .Lgm_fin
	v_add_u32_e32 v67, 0x180000, v64
	global_load_dwordx2 v[132:133], v64, s[34:35] offset:0
	global_load_dwordx2 v[134:135], v64, s[36:37] offset:0
	global_load_dwordx2 v[136:137], v64, s[34:35] offset:32
	global_load_dwordx2 v[138:139], v64, s[36:37] offset:32
	global_load_dwordx2 v[140:141], v64, s[34:35] offset:256
	global_load_dwordx2 v[142:143], v64, s[36:37] offset:256
	global_load_dwordx2 v[144:145], v64, s[34:35] offset:288
	global_load_dwordx2 v[146:147], v64, s[36:37] offset:288
	v_add_u32_e32 v64, 0x30000, v64
	global_load_dwordx2 v[148:149], v64, s[34:35] offset:0
	global_load_dwordx2 v[150:151], v64, s[36:37] offset:0
	global_load_dwordx2 v[152:153], v64, s[34:35] offset:32
	global_load_dwordx2 v[154:155], v64, s[36:37] offset:32
	global_load_dwordx2 v[156:157], v64, s[34:35] offset:256
	global_load_dwordx2 v[158:159], v64, s[36:37] offset:256
	global_load_dwordx2 v[160:161], v64, s[34:35] offset:288
	global_load_dwordx2 v[162:163], v64, s[36:37] offset:288
	v_add_u32_e32 v64, 0x30000, v64
	global_load_dwordx2 v[164:165], v64, s[34:35] offset:0
	global_load_dwordx2 v[166:167], v64, s[36:37] offset:0
	global_load_dwordx2 v[196:197], v64, s[34:35] offset:32
	global_load_dwordx2 v[198:199], v64, s[36:37] offset:32
	global_load_dwordx2 v[200:201], v64, s[34:35] offset:256
	global_load_dwordx2 v[202:203], v64, s[36:37] offset:256
	global_load_dwordx2 v[204:205], v64, s[34:35] offset:288
	global_load_dwordx2 v[206:207], v64, s[36:37] offset:288
	v_add_u32_e32 v64, 0x30000, v64
	global_load_dwordx2 v[208:209], v64, s[34:35] offset:0
	global_load_dwordx2 v[210:211], v64, s[36:37] offset:0
	global_load_dwordx2 v[212:213], v64, s[34:35] offset:32
	global_load_dwordx2 v[214:215], v64, s[36:37] offset:32
	global_load_dwordx2 v[216:217], v64, s[34:35] offset:256
	global_load_dwordx2 v[218:219], v64, s[36:37] offset:256
	global_load_dwordx2 v[220:221], v64, s[34:35] offset:288
	global_load_dwordx2 v[222:223], v64, s[36:37] offset:288
	s_waitcnt vmcnt(30)
	v_lshlrev_b32_e32 v232, 16, v134
	v_and_b32_e32 v233, s30, v134
	v_lshlrev_b32_e32 v234, 16, v135
	v_and_b32_e32 v235, s30, v135
	v_max_f32_e32 v232, s31, v232
	v_max_f32_e32 v233, s31, v233
	v_max_f32_e32 v234, s31, v234
	v_max_f32_e32 v235, s31, v235
	v_rcp_f32_e32 v232, v232
	v_rcp_f32_e32 v233, v233
	v_rcp_f32_e32 v234, v234
	v_rcp_f32_e32 v235, v235
	v_lshlrev_b32_e32 v224, 16, v132
	v_and_b32_e32 v225, s30, v132
	v_lshlrev_b32_e32 v242, 16, v133
	v_and_b32_e32 v243, s30, v133
	v_max_f32_e32 v224, s31, v224
	v_max_f32_e32 v225, s31, v225
	v_max_f32_e32 v242, s31, v242
	v_max_f32_e32 v243, s31, v243
	v_pk_mul_f32 v[232:233], v[232:233], v[224:225]
	v_pk_mul_f32 v[234:235], v[234:235], v[242:243]
	v_pk_mul_f32 v[128:129], v[128:129], v[232:233]
	v_pk_mul_f32 v[130:131], v[130:131], v[234:235]
	global_load_dwordx2 v[132:133], v67, s[34:35] offset:0
	global_load_dwordx2 v[134:135], v67, s[36:37] offset:0
	s_waitcnt vmcnt(30)
	v_lshlrev_b32_e32 v232, 16, v138
	v_and_b32_e32 v233, s30, v138
	v_lshlrev_b32_e32 v234, 16, v139
	v_and_b32_e32 v235, s30, v139
	v_max_f32_e32 v232, s31, v232
	v_max_f32_e32 v233, s31, v233
	v_max_f32_e32 v234, s31, v234
	v_max_f32_e32 v235, s31, v235
	v_rcp_f32_e32 v232, v232
	v_rcp_f32_e32 v233, v233
	v_rcp_f32_e32 v234, v234
	v_rcp_f32_e32 v235, v235
	v_lshlrev_b32_e32 v224, 16, v136
	v_and_b32_e32 v225, s30, v136
	v_lshlrev_b32_e32 v242, 16, v137
	v_and_b32_e32 v243, s30, v137
	v_max_f32_e32 v224, s31, v224
	v_max_f32_e32 v225, s31, v225
	v_max_f32_e32 v242, s31, v242
	v_max_f32_e32 v243, s31, v243
	v_pk_mul_f32 v[232:233], v[232:233], v[224:225]
	v_pk_mul_f32 v[234:235], v[234:235], v[242:243]
	v_pk_mul_f32 v[124:125], v[124:125], v[232:233]
	v_pk_mul_f32 v[126:127], v[126:127], v[234:235]
	global_load_dwordx2 v[136:137], v67, s[34:35] offset:32
	global_load_dwordx2 v[138:139], v67, s[36:37] offset:32
	s_waitcnt vmcnt(30)
	v_lshlrev_b32_e32 v232, 16, v142
	v_and_b32_e32 v233, s30, v142
	v_lshlrev_b32_e32 v234, 16, v143
	v_and_b32_e32 v235, s30, v143
	v_max_f32_e32 v232, s31, v232
	v_max_f32_e32 v233, s31, v233
	v_max_f32_e32 v234, s31, v234
	v_max_f32_e32 v235, s31, v235
	v_rcp_f32_e32 v232, v232
	v_rcp_f32_e32 v233, v233
	v_rcp_f32_e32 v234, v234
	v_rcp_f32_e32 v235, v235
	v_lshlrev_b32_e32 v224, 16, v140
	v_and_b32_e32 v225, s30, v140
	v_lshlrev_b32_e32 v242, 16, v141
	v_and_b32_e32 v243, s30, v141
	v_max_f32_e32 v224, s31, v224
	v_max_f32_e32 v225, s31, v225
	v_max_f32_e32 v242, s31, v242
	v_max_f32_e32 v243, s31, v243
	v_pk_mul_f32 v[232:233], v[232:233], v[224:225]
	v_pk_mul_f32 v[234:235], v[234:235], v[242:243]
	v_pk_mul_f32 v[96:97], v[96:97], v[232:233]
	v_pk_mul_f32 v[98:99], v[98:99], v[234:235]
	global_load_dwordx2 v[140:141], v67, s[34:35] offset:256
	global_load_dwordx2 v[142:143], v67, s[36:37] offset:256
	s_waitcnt vmcnt(30)
; __device__ __forceinline__ u32x2 pack4(f32x4 v) { u32x2 r; r[0] = cvt_pk(v[0], v[1]); r[1] = cvt_pk(v[2], v[3]); return r; }
; __device__ __forceinline__ f32x4 unpack4(u32x2 u) { f32x4 r; r[0] = bflo(u[0]); r[1] = bfhi(u[0]); r[2] = bflo(u[1]); r[3] = bfhi(u[1]); return r; }
; __device__ __forceinline__ void epilogue(const Params& p, const Unit& u, const f32x4 (&acc)[2][2][4][2], int wr, int wc, int fr, int fq) {
;     ...
;   } else if (kind >= 9 && kind <= 11) {
;     const int seg = kind - 9;
;     const bf16_t* gates = (const bf16_t*)(ws + WS_GATES);
;     float* mf = (float*)(ws + WS_MERGED);
;     bf16_t* mb = (bf16_t*)(ws + WS_MERGEDB);
;     const int cb = u.pn * 256 + ct0;
; #pragma unroll
;     for (int ai = 0; ai < 2; ++ai)
; #pragma unroll
;       for (int mp = 0; mp < 2; ++mp) {
;         u32x2 gr[2][2][2]; f32x4 mv[2][2][2];
; #pragma unroll
;         for (int mm = 0; mm < 2; ++mm)
; #pragma unroll
;           for (int bj = 0; bj < 2; ++bj)
; #pragma unroll
;             for (int n = 0; n < 2; ++n) {
;               const size_t row = (size_t)(row0 + ai * 128 + (mp * 2 + mm) * 16);
;               const int col = cb + bj * 128 + n * 16;
;               gr[mm][bj][n] = *(const u32x2*)(gates + row * 6144 + seg * 2048 + col);
;               if (seg > 0) mv[mm][bj][n] = *(const f32x4*)(mf + row * 2048 + col);
;             }
; #pragma unroll
;         for (int mm = 0; mm < 2; ++mm)
; #pragma unroll
;           for (int bj = 0; bj < 2; ++bj)
; #pragma unroll
;             for (int n = 0; n < 2; ++n) {
;               const size_t row = (size_t)(row0 + ai * 128 + (mp * 2 + mm) * 16);
;               const int col = cb + bj * 128 + n * 16;
;               f32x4 v = acc[ai][bj][mp * 2 + mm][n] * unpack4(gr[mm][bj][n]);
;               if (seg > 0) v += mv[mm][bj][n];
;               if (seg < 2) *(f32x4*)(mf + row * 2048 + col) = v;
;               else *(u32x2*)(mb + row * 2048 + col) = pack4(v);
;             }
;       }
	v_lshlrev_b32_e32 v232, 16, v146
	v_and_b32_e32 v233, s30, v146
	v_lshlrev_b32_e32 v234, 16, v147
	v_and_b32_e32 v235, s30, v147
	v_max_f32_e32 v232, s31, v232
	v_max_f32_e32 v233, s31, v233
	v_max_f32_e32 v234, s31, v234
	v_max_f32_e32 v235, s31, v235
	v_rcp_f32_e32 v232, v232
	v_rcp_f32_e32 v233, v233
	v_rcp_f32_e32 v234, v234
	v_rcp_f32_e32 v235, v235
	v_lshlrev_b32_e32 v224, 16, v144
	v_and_b32_e32 v225, s30, v144
	v_lshlrev_b32_e32 v242, 16, v145
	v_and_b32_e32 v243, s30, v145
	v_max_f32_e32 v224, s31, v224
	v_max_f32_e32 v225, s31, v225
	v_max_f32_e32 v242, s31, v242
	v_max_f32_e32 v243, s31, v243
	v_pk_mul_f32 v[232:233], v[232:233], v[224:225]
	v_pk_mul_f32 v[234:235], v[234:235], v[242:243]
	v_pk_mul_f32 v[92:93], v[92:93], v[232:233]
	v_pk_mul_f32 v[94:95], v[94:95], v[234:235]
	global_load_dwordx2 v[144:145], v67, s[34:35] offset:288
	global_load_dwordx2 v[146:147], v67, s[36:37] offset:288
	v_add_u32_e32 v67, 0x30000, v67
	s_waitcnt vmcnt(30)
	v_lshlrev_b32_e32 v232, 16, v150
	v_and_b32_e32 v233, s30, v150
	v_lshlrev_b32_e32 v234, 16, v151
	v_and_b32_e32 v235, s30, v151
	v_max_f32_e32 v232, s31, v232
	v_max_f32_e32 v233, s31, v233
	v_max_f32_e32 v234, s31, v234
	v_max_f32_e32 v235, s31, v235
	v_rcp_f32_e32 v232, v232
	v_rcp_f32_e32 v233, v233
	v_rcp_f32_e32 v234, v234
	v_rcp_f32_e32 v235, v235
	v_lshlrev_b32_e32 v224, 16, v148
	v_and_b32_e32 v225, s30, v148
	v_lshlrev_b32_e32 v242, 16, v149
	v_and_b32_e32 v243, s30, v149
	v_max_f32_e32 v224, s31, v224
	v_max_f32_e32 v225, s31, v225
	v_max_f32_e32 v242, s31, v242
	v_max_f32_e32 v243, s31, v243
	v_pk_mul_f32 v[232:233], v[232:233], v[224:225]
	v_pk_mul_f32 v[234:235], v[234:235], v[242:243]
	v_pk_mul_f32 v[120:121], v[120:121], v[232:233]
	v_pk_mul_f32 v[122:123], v[122:123], v[234:235]
	global_load_dwordx2 v[148:149], v67, s[34:35] offset:0
	global_load_dwordx2 v[150:151], v67, s[36:37] offset:0
	s_waitcnt vmcnt(30)
	v_lshlrev_b32_e32 v232, 16, v154
	v_and_b32_e32 v233, s30, v154
	v_lshlrev_b32_e32 v234, 16, v155
	v_and_b32_e32 v235, s30, v155
	v_max_f32_e32 v232, s31, v232
	v_max_f32_e32 v233, s31, v233
	v_max_f32_e32 v234, s31, v234
	v_max_f32_e32 v235, s31, v235
	v_rcp_f32_e32 v232, v232
	v_rcp_f32_e32 v233, v233
	v_rcp_f32_e32 v234, v234
	v_rcp_f32_e32 v235, v235
	v_lshlrev_b32_e32 v224, 16, v152
	v_and_b32_e32 v225, s30, v152
	v_lshlrev_b32_e32 v242, 16, v153
	v_and_b32_e32 v243, s30, v153
	v_max_f32_e32 v224, s31, v224
	v_max_f32_e32 v225, s31, v225
	v_max_f32_e32 v242, s31, v242
	v_max_f32_e32 v243, s31, v243
	v_pk_mul_f32 v[232:233], v[232:233], v[224:225]
	v_pk_mul_f32 v[234:235], v[234:235], v[242:243]
	v_pk_mul_f32 v[116:117], v[116:117], v[232:233]
	v_pk_mul_f32 v[118:119], v[118:119], v[234:235]
	global_load_dwordx2 v[152:153], v67, s[34:35] offset:32
	global_load_dwordx2 v[154:155], v67, s[36:37] offset:32
	s_waitcnt vmcnt(30)
	v_lshlrev_b32_e32 v232, 16, v158
	v_and_b32_e32 v233, s30, v158
	v_lshlrev_b32_e32 v234, 16, v159
	v_and_b32_e32 v235, s30, v159
	v_max_f32_e32 v232, s31, v232
	v_max_f32_e32 v233, s31, v233
	v_max_f32_e32 v234, s31, v234
	v_max_f32_e32 v235, s31, v235
	v_rcp_f32_e32 v232, v232
	v_rcp_f32_e32 v233, v233
	v_rcp_f32_e32 v234, v234
	v_rcp_f32_e32 v235, v235
	v_lshlrev_b32_e32 v224, 16, v156
	v_and_b32_e32 v225, s30, v156
	v_lshlrev_b32_e32 v242, 16, v157
	v_and_b32_e32 v243, s30, v157
	v_max_f32_e32 v224, s31, v224
	v_max_f32_e32 v225, s31, v225
	v_max_f32_e32 v242, s31, v242
	v_max_f32_e32 v243, s31, v243
	v_pk_mul_f32 v[232:233], v[232:233], v[224:225]
	v_pk_mul_f32 v[234:235], v[234:235], v[242:243]
	v_pk_mul_f32 v[88:89], v[88:89], v[232:233]
	v_pk_mul_f32 v[90:91], v[90:91], v[234:235]
	global_load_dwordx2 v[156:157], v67, s[34:35] offset:256
	global_load_dwordx2 v[158:159], v67, s[36:37] offset:256
	s_waitcnt vmcnt(30)
	v_lshlrev_b32_e32 v232, 16, v162
	v_and_b32_e32 v233, s30, v162
	v_lshlrev_b32_e32 v234, 16, v163
	v_and_b32_e32 v235, s30, v163
	v_max_f32_e32 v232, s31, v232
	v_max_f32_e32 v233, s31, v233
	v_max_f32_e32 v234, s31, v234
	v_max_f32_e32 v235, s31, v235
	v_rcp_f32_e32 v232, v232
	v_rcp_f32_e32 v233, v233
	v_rcp_f32_e32 v234, v234
	v_rcp_f32_e32 v235, v235
	v_lshlrev_b32_e32 v224, 16, v160
	v_and_b32_e32 v225, s30, v160
	v_lshlrev_b32_e32 v242, 16, v161
	v_and_b32_e32 v243, s30, v161
	v_max_f32_e32 v224, s31, v224
	v_max_f32_e32 v225, s31, v225
	v_max_f32_e32 v242, s31, v242
	v_max_f32_e32 v243, s31, v243
	v_pk_mul_f32 v[232:233], v[232:233], v[224:225]
	v_pk_mul_f32 v[234:235], v[234:235], v[242:243]
	v_pk_mul_f32 v[84:85], v[84:85], v[232:233]
	v_pk_mul_f32 v[86:87], v[86:87], v[234:235]
	global_load_dwordx2 v[160:161], v67, s[34:35] offset:288
	global_load_dwordx2 v[162:163], v67, s[36:37] offset:288
	v_add_u32_e32 v67, 0x30000, v67
	s_waitcnt vmcnt(30)
	v_lshlrev_b32_e32 v232, 16, v166
	v_and_b32_e32 v233, s30, v166
	v_lshlrev_b32_e32 v234, 16, v167
	v_and_b32_e32 v235, s30, v167
	v_max_f32_e32 v232, s31, v232
	v_max_f32_e32 v233, s31, v233
	v_max_f32_e32 v234, s31, v234
	v_max_f32_e32 v235, s31, v235
	v_rcp_f32_e32 v232, v232
	v_rcp_f32_e32 v233, v233
	v_rcp_f32_e32 v234, v234
	v_rcp_f32_e32 v235, v235
	v_lshlrev_b32_e32 v224, 16, v164
	v_and_b32_e32 v225, s30, v164
	v_lshlrev_b32_e32 v242, 16, v165
	v_and_b32_e32 v243, s30, v165
	v_max_f32_e32 v224, s31, v224
	v_max_f32_e32 v225, s31, v225
	v_max_f32_e32 v242, s31, v242
	v_max_f32_e32 v243, s31, v243
	v_pk_mul_f32 v[232:233], v[232:233], v[224:225]
	v_pk_mul_f32 v[234:235], v[234:235], v[242:243]
	v_pk_mul_f32 v[112:113], v[112:113], v[232:233]
	v_pk_mul_f32 v[114:115], v[114:115], v[234:235]
	global_load_dwordx2 v[164:165], v67, s[34:35] offset:0
	global_load_dwordx2 v[166:167], v67, s[36:37] offset:0
	s_waitcnt vmcnt(30)
; __device__ __forceinline__ u32x2 pack4(f32x4 v) { u32x2 r; r[0] = cvt_pk(v[0], v[1]); r[1] = cvt_pk(v[2], v[3]); return r; }
; __device__ __forceinline__ f32x4 unpack4(u32x2 u) { f32x4 r; r[0] = bflo(u[0]); r[1] = bfhi(u[0]); r[2] = bflo(u[1]); r[3] = bfhi(u[1]); return r; }
; __device__ __forceinline__ void epilogue(const Params& p, const Unit& u, const f32x4 (&acc)[2][2][4][2], int wr, int wc, int fr, int fq) {
;     ...
;   } else if (kind >= 9 && kind <= 11) {
;     const int seg = kind - 9;
;     const bf16_t* gates = (const bf16_t*)(ws + WS_GATES);
;     float* mf = (float*)(ws + WS_MERGED);
;     bf16_t* mb = (bf16_t*)(ws + WS_MERGEDB);
;     const int cb = u.pn * 256 + ct0;
; #pragma unroll
;     for (int ai = 0; ai < 2; ++ai)
; #pragma unroll
;       for (int mp = 0; mp < 2; ++mp) {
;         u32x2 gr[2][2][2]; f32x4 mv[2][2][2];
; #pragma unroll
;         for (int mm = 0; mm < 2; ++mm)
; #pragma unroll
;           for (int bj = 0; bj < 2; ++bj)
; #pragma unroll
;             for (int n = 0; n < 2; ++n) {
;               const size_t row = (size_t)(row0 + ai * 128 + (mp * 2 + mm) * 16);
;               const int col = cb + bj * 128 + n * 16;
;               gr[mm][bj][n] = *(const u32x2*)(gates + row * 6144 + seg * 2048 + col);
;               if (seg > 0) mv[mm][bj][n] = *(const f32x4*)(mf + row * 2048 + col);
;             }
; #pragma unroll
;         for (int mm = 0; mm < 2; ++mm)
; #pragma unroll
;           for (int bj = 0; bj < 2; ++bj)
; #pragma unroll
;             for (int n = 0; n < 2; ++n) {
;               const size_t row = (size_t)(row0 + ai * 128 + (mp * 2 + mm) * 16);
;               const int col = cb + bj * 128 + n * 16;
;               f32x4 v = acc[ai][bj][mp * 2 + mm][n] * unpack4(gr[mm][bj][n]);
;               if (seg > 0) v += mv[mm][bj][n];
;               if (seg < 2) *(f32x4*)(mf + row * 2048 + col) = v;
;               else *(u32x2*)(mb + row * 2048 + col) = pack4(v);
;             }
;       }
	v_lshlrev_b32_e32 v232, 16, v198
	v_and_b32_e32 v233, s30, v198
	v_lshlrev_b32_e32 v234, 16, v199
	v_and_b32_e32 v235, s30, v199
	v_max_f32_e32 v232, s31, v232
	v_max_f32_e32 v233, s31, v233
	v_max_f32_e32 v234, s31, v234
	v_max_f32_e32 v235, s31, v235
	v_rcp_f32_e32 v232, v232
	v_rcp_f32_e32 v233, v233
	v_rcp_f32_e32 v234, v234
	v_rcp_f32_e32 v235, v235
	v_lshlrev_b32_e32 v224, 16, v196
	v_and_b32_e32 v225, s30, v196
	v_lshlrev_b32_e32 v242, 16, v197
	v_and_b32_e32 v243, s30, v197
	v_max_f32_e32 v224, s31, v224
	v_max_f32_e32 v225, s31, v225
	v_max_f32_e32 v242, s31, v242
	v_max_f32_e32 v243, s31, v243
	v_pk_mul_f32 v[232:233], v[232:233], v[224:225]
	v_pk_mul_f32 v[234:235], v[234:235], v[242:243]
	v_pk_mul_f32 v[108:109], v[108:109], v[232:233]
	v_pk_mul_f32 v[110:111], v[110:111], v[234:235]
	global_load_dwordx2 v[196:197], v67, s[34:35] offset:32
	global_load_dwordx2 v[198:199], v67, s[36:37] offset:32
	s_waitcnt vmcnt(30)
	v_lshlrev_b32_e32 v232, 16, v202
	v_and_b32_e32 v233, s30, v202
	v_lshlrev_b32_e32 v234, 16, v203
	v_and_b32_e32 v235, s30, v203
	v_max_f32_e32 v232, s31, v232
	v_max_f32_e32 v233, s31, v233
	v_max_f32_e32 v234, s31, v234
	v_max_f32_e32 v235, s31, v235
	v_rcp_f32_e32 v232, v232
	v_rcp_f32_e32 v233, v233
	v_rcp_f32_e32 v234, v234
	v_rcp_f32_e32 v235, v235
	v_lshlrev_b32_e32 v224, 16, v200
	v_and_b32_e32 v225, s30, v200
	v_lshlrev_b32_e32 v242, 16, v201
	v_and_b32_e32 v243, s30, v201
	v_max_f32_e32 v224, s31, v224
	v_max_f32_e32 v225, s31, v225
	v_max_f32_e32 v242, s31, v242
	v_max_f32_e32 v243, s31, v243
	v_pk_mul_f32 v[232:233], v[232:233], v[224:225]
	v_pk_mul_f32 v[234:235], v[234:235], v[242:243]
	v_pk_mul_f32 v[80:81], v[80:81], v[232:233]
	v_pk_mul_f32 v[82:83], v[82:83], v[234:235]
	global_load_dwordx2 v[200:201], v67, s[34:35] offset:256
	global_load_dwordx2 v[202:203], v67, s[36:37] offset:256
	s_waitcnt vmcnt(30)
	v_lshlrev_b32_e32 v232, 16, v206
	v_and_b32_e32 v233, s30, v206
	v_lshlrev_b32_e32 v234, 16, v207
	v_and_b32_e32 v235, s30, v207
	v_max_f32_e32 v232, s31, v232
	v_max_f32_e32 v233, s31, v233
	v_max_f32_e32 v234, s31, v234
	v_max_f32_e32 v235, s31, v235
	v_rcp_f32_e32 v232, v232
	v_rcp_f32_e32 v233, v233
	v_rcp_f32_e32 v234, v234
	v_rcp_f32_e32 v235, v235
	v_lshlrev_b32_e32 v224, 16, v204
	v_and_b32_e32 v225, s30, v204
	v_lshlrev_b32_e32 v242, 16, v205
	v_and_b32_e32 v243, s30, v205
	v_max_f32_e32 v224, s31, v224
	v_max_f32_e32 v225, s31, v225
	v_max_f32_e32 v242, s31, v242
	v_max_f32_e32 v243, s31, v243
	v_pk_mul_f32 v[232:233], v[232:233], v[224:225]
	v_pk_mul_f32 v[234:235], v[234:235], v[242:243]
	v_pk_mul_f32 v[76:77], v[76:77], v[232:233]
	v_pk_mul_f32 v[78:79], v[78:79], v[234:235]
	global_load_dwordx2 v[204:205], v67, s[34:35] offset:288
	global_load_dwordx2 v[206:207], v67, s[36:37] offset:288
	v_add_u32_e32 v67, 0x30000, v67
	s_waitcnt vmcnt(30)
	v_lshlrev_b32_e32 v232, 16, v210
	v_and_b32_e32 v233, s30, v210
	v_lshlrev_b32_e32 v234, 16, v211
	v_and_b32_e32 v235, s30, v211
	v_max_f32_e32 v232, s31, v232
	v_max_f32_e32 v233, s31, v233
	v_max_f32_e32 v234, s31, v234
	v_max_f32_e32 v235, s31, v235
	v_rcp_f32_e32 v232, v232
	v_rcp_f32_e32 v233, v233
	v_rcp_f32_e32 v234, v234
	v_rcp_f32_e32 v235, v235
	v_lshlrev_b32_e32 v224, 16, v208
	v_and_b32_e32 v225, s30, v208
	v_lshlrev_b32_e32 v242, 16, v209
	v_and_b32_e32 v243, s30, v209
	v_max_f32_e32 v224, s31, v224
	v_max_f32_e32 v225, s31, v225
	v_max_f32_e32 v242, s31, v242
	v_max_f32_e32 v243, s31, v243
	v_pk_mul_f32 v[232:233], v[232:233], v[224:225]
	v_pk_mul_f32 v[234:235], v[234:235], v[242:243]
	v_pk_mul_f32 v[104:105], v[104:105], v[232:233]
	v_pk_mul_f32 v[106:107], v[106:107], v[234:235]
	global_load_dwordx2 v[208:209], v67, s[34:35] offset:0
	global_load_dwordx2 v[210:211], v67, s[36:37] offset:0
	s_waitcnt vmcnt(30)
	v_lshlrev_b32_e32 v232, 16, v214
	v_and_b32_e32 v233, s30, v214
	v_lshlrev_b32_e32 v234, 16, v215
	v_and_b32_e32 v235, s30, v215
	v_max_f32_e32 v232, s31, v232
	v_max_f32_e32 v233, s31, v233
	v_max_f32_e32 v234, s31, v234
	v_max_f32_e32 v235, s31, v235
	v_rcp_f32_e32 v232, v232
	v_rcp_f32_e32 v233, v233
	v_rcp_f32_e32 v234, v234
	v_rcp_f32_e32 v235, v235
	v_lshlrev_b32_e32 v224, 16, v212
	v_and_b32_e32 v225, s30, v212
	v_lshlrev_b32_e32 v242, 16, v213
	v_and_b32_e32 v243, s30, v213
	v_max_f32_e32 v224, s31, v224
	v_max_f32_e32 v225, s31, v225
	v_max_f32_e32 v242, s31, v242
	v_max_f32_e32 v243, s31, v243
	v_pk_mul_f32 v[232:233], v[232:233], v[224:225]
	v_pk_mul_f32 v[234:235], v[234:235], v[242:243]
	v_pk_mul_f32 v[100:101], v[100:101], v[232:233]
	v_pk_mul_f32 v[102:103], v[102:103], v[234:235]
	global_load_dwordx2 v[212:213], v67, s[34:35] offset:32
	global_load_dwordx2 v[214:215], v67, s[36:37] offset:32
	s_waitcnt vmcnt(30)
	v_lshlrev_b32_e32 v232, 16, v218
	v_and_b32_e32 v233, s30, v218
	v_lshlrev_b32_e32 v234, 16, v219
	v_and_b32_e32 v235, s30, v219
	v_max_f32_e32 v232, s31, v232
	v_max_f32_e32 v233, s31, v233
	v_max_f32_e32 v234, s31, v234
	v_max_f32_e32 v235, s31, v235
	v_rcp_f32_e32 v232, v232
	v_rcp_f32_e32 v233, v233
	v_rcp_f32_e32 v234, v234
	v_rcp_f32_e32 v235, v235
	v_lshlrev_b32_e32 v224, 16, v216
	v_and_b32_e32 v225, s30, v216
	v_lshlrev_b32_e32 v242, 16, v217
	v_and_b32_e32 v243, s30, v217
	v_max_f32_e32 v224, s31, v224
	v_max_f32_e32 v225, s31, v225
	v_max_f32_e32 v242, s31, v242
	v_max_f32_e32 v243, s31, v243
	v_pk_mul_f32 v[232:233], v[232:233], v[224:225]
	v_pk_mul_f32 v[234:235], v[234:235], v[242:243]
	v_pk_mul_f32 v[72:73], v[72:73], v[232:233]
	v_pk_mul_f32 v[74:75], v[74:75], v[234:235]
	global_load_dwordx2 v[216:217], v67, s[34:35] offset:256
	global_load_dwordx2 v[218:219], v67, s[36:37] offset:256
	s_waitcnt vmcnt(30)
; __device__ __forceinline__ u32x2 pack4(f32x4 v) { u32x2 r; r[0] = cvt_pk(v[0], v[1]); r[1] = cvt_pk(v[2], v[3]); return r; }
; __device__ __forceinline__ f32x4 unpack4(u32x2 u) { f32x4 r; r[0] = bflo(u[0]); r[1] = bfhi(u[0]); r[2] = bflo(u[1]); r[3] = bfhi(u[1]); return r; }
; __device__ __forceinline__ void epilogue(const Params& p, const Unit& u, const f32x4 (&acc)[2][2][4][2], int wr, int wc, int fr, int fq) {
;     ...
;   } else if (kind >= 9 && kind <= 11) {
;     const int seg = kind - 9;
;     const bf16_t* gates = (const bf16_t*)(ws + WS_GATES);
;     float* mf = (float*)(ws + WS_MERGED);
;     bf16_t* mb = (bf16_t*)(ws + WS_MERGEDB);
;     const int cb = u.pn * 256 + ct0;
; #pragma unroll
;     for (int ai = 0; ai < 2; ++ai)
; #pragma unroll
;       for (int mp = 0; mp < 2; ++mp) {
;         u32x2 gr[2][2][2]; f32x4 mv[2][2][2];
; #pragma unroll
;         for (int mm = 0; mm < 2; ++mm)
; #pragma unroll
;           for (int bj = 0; bj < 2; ++bj)
; #pragma unroll
;             for (int n = 0; n < 2; ++n) {
;               const size_t row = (size_t)(row0 + ai * 128 + (mp * 2 + mm) * 16);
;               const int col = cb + bj * 128 + n * 16;
;               gr[mm][bj][n] = *(const u32x2*)(gates + row * 6144 + seg * 2048 + col);
;               if (seg > 0) mv[mm][bj][n] = *(const f32x4*)(mf + row * 2048 + col);
;             }
; #pragma unroll
;         for (int mm = 0; mm < 2; ++mm)
; #pragma unroll
;           for (int bj = 0; bj < 2; ++bj)
; #pragma unroll
;             for (int n = 0; n < 2; ++n) {
;               const size_t row = (size_t)(row0 + ai * 128 + (mp * 2 + mm) * 16);
;               const int col = cb + bj * 128 + n * 16;
;               f32x4 v = acc[ai][bj][mp * 2 + mm][n] * unpack4(gr[mm][bj][n]);
;               if (seg > 0) v += mv[mm][bj][n];
;               if (seg < 2) *(f32x4*)(mf + row * 2048 + col) = v;
;               else *(u32x2*)(mb + row * 2048 + col) = pack4(v);
;             }
;       }
	v_lshlrev_b32_e32 v232, 16, v222
	v_and_b32_e32 v233, s30, v222
	v_lshlrev_b32_e32 v234, 16, v223
	v_and_b32_e32 v235, s30, v223
	v_max_f32_e32 v232, s31, v232
	v_max_f32_e32 v233, s31, v233
	v_max_f32_e32 v234, s31, v234
	v_max_f32_e32 v235, s31, v235
	v_rcp_f32_e32 v232, v232
	v_rcp_f32_e32 v233, v233
	v_rcp_f32_e32 v234, v234
	v_rcp_f32_e32 v235, v235
	v_lshlrev_b32_e32 v224, 16, v220
	v_and_b32_e32 v225, s30, v220
	v_lshlrev_b32_e32 v242, 16, v221
	v_and_b32_e32 v243, s30, v221
	v_max_f32_e32 v224, s31, v224
	v_max_f32_e32 v225, s31, v225
	v_max_f32_e32 v242, s31, v242
	v_max_f32_e32 v243, s31, v243
	v_pk_mul_f32 v[232:233], v[232:233], v[224:225]
	v_pk_mul_f32 v[234:235], v[234:235], v[242:243]
	v_pk_mul_f32 v[68:69], v[68:69], v[232:233]
	v_pk_mul_f32 v[70:71], v[70:71], v[234:235]
	global_load_dwordx2 v[220:221], v67, s[34:35] offset:288
	global_load_dwordx2 v[222:223], v67, s[36:37] offset:288
	s_waitcnt vmcnt(30)
	v_lshlrev_b32_e32 v232, 16, v134
	v_and_b32_e32 v233, s30, v134
	v_lshlrev_b32_e32 v234, 16, v135
	v_and_b32_e32 v235, s30, v135
	v_max_f32_e32 v232, s31, v232
	v_max_f32_e32 v233, s31, v233
	v_max_f32_e32 v234, s31, v234
	v_max_f32_e32 v235, s31, v235
	v_rcp_f32_e32 v232, v232
	v_rcp_f32_e32 v233, v233
	v_rcp_f32_e32 v234, v234
	v_rcp_f32_e32 v235, v235
	v_lshlrev_b32_e32 v224, 16, v132
	v_and_b32_e32 v225, s30, v132
	v_lshlrev_b32_e32 v242, 16, v133
	v_and_b32_e32 v243, s30, v133
	v_max_f32_e32 v224, s31, v224
	v_max_f32_e32 v225, s31, v225
	v_max_f32_e32 v242, s31, v242
	v_max_f32_e32 v243, s31, v243
	v_pk_mul_f32 v[232:233], v[232:233], v[224:225]
	v_pk_mul_f32 v[234:235], v[234:235], v[242:243]
	v_pk_mul_f32 v[60:61], v[60:61], v[232:233]
	v_pk_mul_f32 v[62:63], v[62:63], v[234:235]
	s_waitcnt vmcnt(28)
	v_lshlrev_b32_e32 v232, 16, v138
	v_and_b32_e32 v233, s30, v138
	v_lshlrev_b32_e32 v234, 16, v139
	v_and_b32_e32 v235, s30, v139
	v_max_f32_e32 v232, s31, v232
	v_max_f32_e32 v233, s31, v233
	v_max_f32_e32 v234, s31, v234
	v_max_f32_e32 v235, s31, v235
	v_rcp_f32_e32 v232, v232
	v_rcp_f32_e32 v233, v233
	v_rcp_f32_e32 v234, v234
	v_rcp_f32_e32 v235, v235
	v_lshlrev_b32_e32 v224, 16, v136
	v_and_b32_e32 v225, s30, v136
	v_lshlrev_b32_e32 v242, 16, v137
	v_and_b32_e32 v243, s30, v137
	v_max_f32_e32 v224, s31, v224
	v_max_f32_e32 v225, s31, v225
	v_max_f32_e32 v242, s31, v242
	v_max_f32_e32 v243, s31, v243
	v_pk_mul_f32 v[232:233], v[232:233], v[224:225]
	v_pk_mul_f32 v[234:235], v[234:235], v[242:243]
	v_pk_mul_f32 v[56:57], v[56:57], v[232:233]
	v_pk_mul_f32 v[58:59], v[58:59], v[234:235]
	s_waitcnt vmcnt(26)
	v_lshlrev_b32_e32 v232, 16, v142
	v_and_b32_e32 v233, s30, v142
	v_lshlrev_b32_e32 v234, 16, v143
	v_and_b32_e32 v235, s30, v143
	v_max_f32_e32 v232, s31, v232
	v_max_f32_e32 v233, s31, v233
	v_max_f32_e32 v234, s31, v234
	v_max_f32_e32 v235, s31, v235
	v_rcp_f32_e32 v232, v232
	v_rcp_f32_e32 v233, v233
	v_rcp_f32_e32 v234, v234
	v_rcp_f32_e32 v235, v235
	v_lshlrev_b32_e32 v224, 16, v140
	v_and_b32_e32 v225, s30, v140
	v_lshlrev_b32_e32 v242, 16, v141
	v_and_b32_e32 v243, s30, v141
	v_max_f32_e32 v224, s31, v224
	v_max_f32_e32 v225, s31, v225
	v_max_f32_e32 v242, s31, v242
	v_max_f32_e32 v243, s31, v243
	v_pk_mul_f32 v[232:233], v[232:233], v[224:225]
	v_pk_mul_f32 v[234:235], v[234:235], v[242:243]
	v_pk_mul_f32 v[28:29], v[28:29], v[232:233]
	v_pk_mul_f32 v[30:31], v[30:31], v[234:235]
	s_waitcnt vmcnt(24)
	v_lshlrev_b32_e32 v232, 16, v146
	v_and_b32_e32 v233, s30, v146
	v_lshlrev_b32_e32 v234, 16, v147
	v_and_b32_e32 v235, s30, v147
	v_max_f32_e32 v232, s31, v232
	v_max_f32_e32 v233, s31, v233
	v_max_f32_e32 v234, s31, v234
	v_max_f32_e32 v235, s31, v235
	v_rcp_f32_e32 v232, v232
	v_rcp_f32_e32 v233, v233
	v_rcp_f32_e32 v234, v234
	v_rcp_f32_e32 v235, v235
	v_lshlrev_b32_e32 v224, 16, v144
	v_and_b32_e32 v225, s30, v144
	v_lshlrev_b32_e32 v242, 16, v145
	v_and_b32_e32 v243, s30, v145
	v_max_f32_e32 v224, s31, v224
	v_max_f32_e32 v225, s31, v225
	v_max_f32_e32 v242, s31, v242
	v_max_f32_e32 v243, s31, v243
	v_pk_mul_f32 v[232:233], v[232:233], v[224:225]
	v_pk_mul_f32 v[234:235], v[234:235], v[242:243]
	v_pk_mul_f32 v[24:25], v[24:25], v[232:233]
	v_pk_mul_f32 v[26:27], v[26:27], v[234:235]
	s_waitcnt vmcnt(22)
	v_lshlrev_b32_e32 v232, 16, v150
	v_and_b32_e32 v233, s30, v150
	v_lshlrev_b32_e32 v234, 16, v151
	v_and_b32_e32 v235, s30, v151
	v_max_f32_e32 v232, s31, v232
	v_max_f32_e32 v233, s31, v233
	v_max_f32_e32 v234, s31, v234
	v_max_f32_e32 v235, s31, v235
	v_rcp_f32_e32 v232, v232
	v_rcp_f32_e32 v233, v233
	v_rcp_f32_e32 v234, v234
	v_rcp_f32_e32 v235, v235
	v_lshlrev_b32_e32 v224, 16, v148
	v_and_b32_e32 v225, s30, v148
	v_lshlrev_b32_e32 v242, 16, v149
	v_and_b32_e32 v243, s30, v149
	v_max_f32_e32 v224, s31, v224
	v_max_f32_e32 v225, s31, v225
	v_max_f32_e32 v242, s31, v242
	v_max_f32_e32 v243, s31, v243
	v_pk_mul_f32 v[232:233], v[232:233], v[224:225]
	v_pk_mul_f32 v[234:235], v[234:235], v[242:243]
	v_pk_mul_f32 v[52:53], v[52:53], v[232:233]
	v_pk_mul_f32 v[54:55], v[54:55], v[234:235]
	s_waitcnt vmcnt(20)
	v_lshlrev_b32_e32 v232, 16, v154
	v_and_b32_e32 v233, s30, v154
	v_lshlrev_b32_e32 v234, 16, v155
	v_and_b32_e32 v235, s30, v155
	v_max_f32_e32 v232, s31, v232
	v_max_f32_e32 v233, s31, v233
	v_max_f32_e32 v234, s31, v234
	v_max_f32_e32 v235, s31, v235
	v_rcp_f32_e32 v232, v232
	v_rcp_f32_e32 v233, v233
	v_rcp_f32_e32 v234, v234
	v_rcp_f32_e32 v235, v235
	v_lshlrev_b32_e32 v224, 16, v152
	v_and_b32_e32 v225, s30, v152
	v_lshlrev_b32_e32 v242, 16, v153
	v_and_b32_e32 v243, s30, v153
	v_max_f32_e32 v224, s31, v224
	v_max_f32_e32 v225, s31, v225
	v_max_f32_e32 v242, s31, v242
	v_max_f32_e32 v243, s31, v243
	v_pk_mul_f32 v[232:233], v[232:233], v[224:225]
	v_pk_mul_f32 v[234:235], v[234:235], v[242:243]
	v_pk_mul_f32 v[48:49], v[48:49], v[232:233]
	v_pk_mul_f32 v[50:51], v[50:51], v[234:235]
	s_waitcnt vmcnt(18)
; __device__ __forceinline__ u32x2 pack4(f32x4 v) { u32x2 r; r[0] = cvt_pk(v[0], v[1]); r[1] = cvt_pk(v[2], v[3]); return r; }
; __device__ __forceinline__ f32x4 unpack4(u32x2 u) { f32x4 r; r[0] = bflo(u[0]); r[1] = bfhi(u[0]); r[2] = bflo(u[1]); r[3] = bfhi(u[1]); return r; }
; __device__ __forceinline__ void epilogue(const Params& p, const Unit& u, const f32x4 (&acc)[2][2][4][2], int wr, int wc, int fr, int fq) {
;     ...
;   } else if (kind >= 9 && kind <= 11) {
;     const int seg = kind - 9;
;     const bf16_t* gates = (const bf16_t*)(ws + WS_GATES);
;     float* mf = (float*)(ws + WS_MERGED);
;     bf16_t* mb = (bf16_t*)(ws + WS_MERGEDB);
;     const int cb = u.pn * 256 + ct0;
; #pragma unroll
;     for (int ai = 0; ai < 2; ++ai)
; #pragma unroll
;       for (int mp = 0; mp < 2; ++mp) {
;         u32x2 gr[2][2][2]; f32x4 mv[2][2][2];
; #pragma unroll
;         for (int mm = 0; mm < 2; ++mm)
; #pragma unroll
;           for (int bj = 0; bj < 2; ++bj)
; #pragma unroll
;             for (int n = 0; n < 2; ++n) {
;               const size_t row = (size_t)(row0 + ai * 128 + (mp * 2 + mm) * 16);
;               const int col = cb + bj * 128 + n * 16;
;               gr[mm][bj][n] = *(const u32x2*)(gates + row * 6144 + seg * 2048 + col);
;               if (seg > 0) mv[mm][bj][n] = *(const f32x4*)(mf + row * 2048 + col);
;             }
; #pragma unroll
;         for (int mm = 0; mm < 2; ++mm)
; #pragma unroll
;           for (int bj = 0; bj < 2; ++bj)
; #pragma unroll
;             for (int n = 0; n < 2; ++n) {
;               const size_t row = (size_t)(row0 + ai * 128 + (mp * 2 + mm) * 16);
;               const int col = cb + bj * 128 + n * 16;
;               f32x4 v = acc[ai][bj][mp * 2 + mm][n] * unpack4(gr[mm][bj][n]);
;               if (seg > 0) v += mv[mm][bj][n];
;               if (seg < 2) *(f32x4*)(mf + row * 2048 + col) = v;
;               else *(u32x2*)(mb + row * 2048 + col) = pack4(v);
;             }
;       }
	v_lshlrev_b32_e32 v232, 16, v158
	v_and_b32_e32 v233, s30, v158
	v_lshlrev_b32_e32 v234, 16, v159
	v_and_b32_e32 v235, s30, v159
	v_max_f32_e32 v232, s31, v232
	v_max_f32_e32 v233, s31, v233
	v_max_f32_e32 v234, s31, v234
	v_max_f32_e32 v235, s31, v235
	v_rcp_f32_e32 v232, v232
	v_rcp_f32_e32 v233, v233
	v_rcp_f32_e32 v234, v234
	v_rcp_f32_e32 v235, v235
	v_lshlrev_b32_e32 v224, 16, v156
	v_and_b32_e32 v225, s30, v156
	v_lshlrev_b32_e32 v242, 16, v157
	v_and_b32_e32 v243, s30, v157
	v_max_f32_e32 v224, s31, v224
	v_max_f32_e32 v225, s31, v225
	v_max_f32_e32 v242, s31, v242
	v_max_f32_e32 v243, s31, v243
	v_pk_mul_f32 v[232:233], v[232:233], v[224:225]
	v_pk_mul_f32 v[234:235], v[234:235], v[242:243]
	v_pk_mul_f32 v[20:21], v[20:21], v[232:233]
	v_pk_mul_f32 v[22:23], v[22:23], v[234:235]
	s_waitcnt vmcnt(16)
	v_lshlrev_b32_e32 v232, 16, v162
	v_and_b32_e32 v233, s30, v162
	v_lshlrev_b32_e32 v234, 16, v163
	v_and_b32_e32 v235, s30, v163
	v_max_f32_e32 v232, s31, v232
	v_max_f32_e32 v233, s31, v233
	v_max_f32_e32 v234, s31, v234
	v_max_f32_e32 v235, s31, v235
	v_rcp_f32_e32 v232, v232
	v_rcp_f32_e32 v233, v233
	v_rcp_f32_e32 v234, v234
	v_rcp_f32_e32 v235, v235
	v_lshlrev_b32_e32 v224, 16, v160
	v_and_b32_e32 v225, s30, v160
	v_lshlrev_b32_e32 v242, 16, v161
	v_and_b32_e32 v243, s30, v161
	v_max_f32_e32 v224, s31, v224
	v_max_f32_e32 v225, s31, v225
	v_max_f32_e32 v242, s31, v242
	v_max_f32_e32 v243, s31, v243
	v_pk_mul_f32 v[232:233], v[232:233], v[224:225]
	v_pk_mul_f32 v[234:235], v[234:235], v[242:243]
	v_pk_mul_f32 v[16:17], v[16:17], v[232:233]
	v_pk_mul_f32 v[18:19], v[18:19], v[234:235]
	s_waitcnt vmcnt(14)
	v_lshlrev_b32_e32 v232, 16, v166
	v_and_b32_e32 v233, s30, v166
	v_lshlrev_b32_e32 v234, 16, v167
	v_and_b32_e32 v235, s30, v167
	v_max_f32_e32 v232, s31, v232
	v_max_f32_e32 v233, s31, v233
	v_max_f32_e32 v234, s31, v234
	v_max_f32_e32 v235, s31, v235
	v_rcp_f32_e32 v232, v232
	v_rcp_f32_e32 v233, v233
	v_rcp_f32_e32 v234, v234
	v_rcp_f32_e32 v235, v235
	v_lshlrev_b32_e32 v224, 16, v164
	v_and_b32_e32 v225, s30, v164
	v_lshlrev_b32_e32 v242, 16, v165
	v_and_b32_e32 v243, s30, v165
	v_max_f32_e32 v224, s31, v224
	v_max_f32_e32 v225, s31, v225
	v_max_f32_e32 v242, s31, v242
	v_max_f32_e32 v243, s31, v243
	v_pk_mul_f32 v[232:233], v[232:233], v[224:225]
	v_pk_mul_f32 v[234:235], v[234:235], v[242:243]
	v_pk_mul_f32 v[44:45], v[44:45], v[232:233]
	v_pk_mul_f32 v[46:47], v[46:47], v[234:235]
	s_waitcnt vmcnt(12)
	v_lshlrev_b32_e32 v232, 16, v198
	v_and_b32_e32 v233, s30, v198
	v_lshlrev_b32_e32 v234, 16, v199
	v_and_b32_e32 v235, s30, v199
	v_max_f32_e32 v232, s31, v232
	v_max_f32_e32 v233, s31, v233
	v_max_f32_e32 v234, s31, v234
	v_max_f32_e32 v235, s31, v235
	v_rcp_f32_e32 v232, v232
	v_rcp_f32_e32 v233, v233
	v_rcp_f32_e32 v234, v234
	v_rcp_f32_e32 v235, v235
	v_lshlrev_b32_e32 v224, 16, v196
	v_and_b32_e32 v225, s30, v196
	v_lshlrev_b32_e32 v242, 16, v197
	v_and_b32_e32 v243, s30, v197
	v_max_f32_e32 v224, s31, v224
	v_max_f32_e32 v225, s31, v225
	v_max_f32_e32 v242, s31, v242
	v_max_f32_e32 v243, s31, v243
	v_pk_mul_f32 v[232:233], v[232:233], v[224:225]
	v_pk_mul_f32 v[234:235], v[234:235], v[242:243]
	v_pk_mul_f32 v[40:41], v[40:41], v[232:233]
	v_pk_mul_f32 v[42:43], v[42:43], v[234:235]
	s_waitcnt vmcnt(10)
	v_lshlrev_b32_e32 v232, 16, v202
	v_and_b32_e32 v233, s30, v202
	v_lshlrev_b32_e32 v234, 16, v203
	v_and_b32_e32 v235, s30, v203
	v_max_f32_e32 v232, s31, v232
	v_max_f32_e32 v233, s31, v233
	v_max_f32_e32 v234, s31, v234
	v_max_f32_e32 v235, s31, v235
	v_rcp_f32_e32 v232, v232
	v_rcp_f32_e32 v233, v233
	v_rcp_f32_e32 v234, v234
	v_rcp_f32_e32 v235, v235
	v_lshlrev_b32_e32 v224, 16, v200
	v_and_b32_e32 v225, s30, v200
	v_lshlrev_b32_e32 v242, 16, v201
	v_and_b32_e32 v243, s30, v201
	v_max_f32_e32 v224, s31, v224
	v_max_f32_e32 v225, s31, v225
	v_max_f32_e32 v242, s31, v242
	v_max_f32_e32 v243, s31, v243
	v_pk_mul_f32 v[232:233], v[232:233], v[224:225]
	v_pk_mul_f32 v[234:235], v[234:235], v[242:243]
	v_pk_mul_f32 v[12:13], v[12:13], v[232:233]
	v_pk_mul_f32 v[14:15], v[14:15], v[234:235]
	s_waitcnt vmcnt(8)
	v_lshlrev_b32_e32 v232, 16, v206
	v_and_b32_e32 v233, s30, v206
	v_lshlrev_b32_e32 v234, 16, v207
	v_and_b32_e32 v235, s30, v207
	v_max_f32_e32 v232, s31, v232
	v_max_f32_e32 v233, s31, v233
	v_max_f32_e32 v234, s31, v234
	v_max_f32_e32 v235, s31, v235
	v_rcp_f32_e32 v232, v232
	v_rcp_f32_e32 v233, v233
	v_rcp_f32_e32 v234, v234
	v_rcp_f32_e32 v235, v235
	v_lshlrev_b32_e32 v224, 16, v204
	v_and_b32_e32 v225, s30, v204
	v_lshlrev_b32_e32 v242, 16, v205
	v_and_b32_e32 v243, s30, v205
	v_max_f32_e32 v224, s31, v224
	v_max_f32_e32 v225, s31, v225
	v_max_f32_e32 v242, s31, v242
	v_max_f32_e32 v243, s31, v243
	v_pk_mul_f32 v[232:233], v[232:233], v[224:225]
	v_pk_mul_f32 v[234:235], v[234:235], v[242:243]
	v_pk_mul_f32 v[8:9], v[8:9], v[232:233]
	v_pk_mul_f32 v[10:11], v[10:11], v[234:235]
	s_waitcnt vmcnt(6)
	v_lshlrev_b32_e32 v232, 16, v210
	v_and_b32_e32 v233, s30, v210
	v_lshlrev_b32_e32 v234, 16, v211
	v_and_b32_e32 v235, s30, v211
	v_max_f32_e32 v232, s31, v232
	v_max_f32_e32 v233, s31, v233
	v_max_f32_e32 v234, s31, v234
	v_max_f32_e32 v235, s31, v235
	v_rcp_f32_e32 v232, v232
	v_rcp_f32_e32 v233, v233
	v_rcp_f32_e32 v234, v234
	v_rcp_f32_e32 v235, v235
	v_lshlrev_b32_e32 v224, 16, v208
	v_and_b32_e32 v225, s30, v208
	v_lshlrev_b32_e32 v242, 16, v209
	v_and_b32_e32 v243, s30, v209
	v_max_f32_e32 v224, s31, v224
	v_max_f32_e32 v225, s31, v225
	v_max_f32_e32 v242, s31, v242
	v_max_f32_e32 v243, s31, v243
	v_pk_mul_f32 v[232:233], v[232:233], v[224:225]
	v_pk_mul_f32 v[234:235], v[234:235], v[242:243]
	v_pk_mul_f32 v[36:37], v[36:37], v[232:233]
	v_pk_mul_f32 v[38:39], v[38:39], v[234:235]
	s_waitcnt vmcnt(4)
; __device__ __forceinline__ u32x2 pack4(f32x4 v) { u32x2 r; r[0] = cvt_pk(v[0], v[1]); r[1] = cvt_pk(v[2], v[3]); return r; }
; __device__ __forceinline__ f32x4 unpack4(u32x2 u) { f32x4 r; r[0] = bflo(u[0]); r[1] = bfhi(u[0]); r[2] = bflo(u[1]); r[3] = bfhi(u[1]); return r; }
; __device__ __forceinline__ void epilogue(const Params& p, const Unit& u, const f32x4 (&acc)[2][2][4][2], int wr, int wc, int fr, int fq) {
;     ...
;   } else if (kind >= 9 && kind <= 11) {
;     const int seg = kind - 9;
;     const bf16_t* gates = (const bf16_t*)(ws + WS_GATES);
;     float* mf = (float*)(ws + WS_MERGED);
;     bf16_t* mb = (bf16_t*)(ws + WS_MERGEDB);
;     const int cb = u.pn * 256 + ct0;
; #pragma unroll
;     for (int ai = 0; ai < 2; ++ai)
; #pragma unroll
;       for (int mp = 0; mp < 2; ++mp) {
;         u32x2 gr[2][2][2]; f32x4 mv[2][2][2];
; #pragma unroll
;         for (int mm = 0; mm < 2; ++mm)
; #pragma unroll
;           for (int bj = 0; bj < 2; ++bj)
; #pragma unroll
;             for (int n = 0; n < 2; ++n) {
;               const size_t row = (size_t)(row0 + ai * 128 + (mp * 2 + mm) * 16);
;               const int col = cb + bj * 128 + n * 16;
;               gr[mm][bj][n] = *(const u32x2*)(gates + row * 6144 + seg * 2048 + col);
;               if (seg > 0) mv[mm][bj][n] = *(const f32x4*)(mf + row * 2048 + col);
;             }
; #pragma unroll
;         for (int mm = 0; mm < 2; ++mm)
; #pragma unroll
;           for (int bj = 0; bj < 2; ++bj)
; #pragma unroll
;             for (int n = 0; n < 2; ++n) {
;               const size_t row = (size_t)(row0 + ai * 128 + (mp * 2 + mm) * 16);
;               const int col = cb + bj * 128 + n * 16;
;               f32x4 v = acc[ai][bj][mp * 2 + mm][n] * unpack4(gr[mm][bj][n]);
;               if (seg > 0) v += mv[mm][bj][n];
;               if (seg < 2) *(f32x4*)(mf + row * 2048 + col) = v;
;               else *(u32x2*)(mb + row * 2048 + col) = pack4(v);
;             }
;       }
; __device__ __forceinline__ void gemm_phase(const Params& p, LAS unsigned char* lds, int gph, unsigned ldB  ) {
;     ...
;     cur = nxt; cA = nA; cB = nB; ++ui;
	v_lshlrev_b32_e32 v232, 16, v214
	v_and_b32_e32 v233, s30, v214
	v_lshlrev_b32_e32 v234, 16, v215
	v_and_b32_e32 v235, s30, v215
	v_max_f32_e32 v232, s31, v232
	v_max_f32_e32 v233, s31, v233
	v_max_f32_e32 v234, s31, v234
	v_max_f32_e32 v235, s31, v235
	v_rcp_f32_e32 v232, v232
	v_rcp_f32_e32 v233, v233
	v_rcp_f32_e32 v234, v234
	v_rcp_f32_e32 v235, v235
	v_lshlrev_b32_e32 v224, 16, v212
	v_and_b32_e32 v225, s30, v212
	v_lshlrev_b32_e32 v242, 16, v213
	v_and_b32_e32 v243, s30, v213
	v_max_f32_e32 v224, s31, v224
	v_max_f32_e32 v225, s31, v225
	v_max_f32_e32 v242, s31, v242
	v_max_f32_e32 v243, s31, v243
	v_pk_mul_f32 v[232:233], v[232:233], v[224:225]
	v_pk_mul_f32 v[234:235], v[234:235], v[242:243]
	v_pk_mul_f32 v[32:33], v[32:33], v[232:233]
	v_pk_mul_f32 v[34:35], v[34:35], v[234:235]
	s_waitcnt vmcnt(2)
	v_lshlrev_b32_e32 v232, 16, v218
	v_and_b32_e32 v233, s30, v218
	v_lshlrev_b32_e32 v234, 16, v219
	v_and_b32_e32 v235, s30, v219
	v_max_f32_e32 v232, s31, v232
	v_max_f32_e32 v233, s31, v233
	v_max_f32_e32 v234, s31, v234
	v_max_f32_e32 v235, s31, v235
	v_rcp_f32_e32 v232, v232
	v_rcp_f32_e32 v233, v233
	v_rcp_f32_e32 v234, v234
	v_rcp_f32_e32 v235, v235
	v_lshlrev_b32_e32 v224, 16, v216
	v_and_b32_e32 v225, s30, v216
	v_lshlrev_b32_e32 v242, 16, v217
	v_and_b32_e32 v243, s30, v217
	v_max_f32_e32 v224, s31, v224
	v_max_f32_e32 v225, s31, v225
	v_max_f32_e32 v242, s31, v242
	v_max_f32_e32 v243, s31, v243
	v_pk_mul_f32 v[232:233], v[232:233], v[224:225]
	v_pk_mul_f32 v[234:235], v[234:235], v[242:243]
	v_pk_mul_f32 v[4:5], v[4:5], v[232:233]
	v_pk_mul_f32 v[6:7], v[6:7], v[234:235]
	s_waitcnt vmcnt(0)
	v_lshlrev_b32_e32 v232, 16, v222
	v_and_b32_e32 v233, s30, v222
	v_lshlrev_b32_e32 v234, 16, v223
	v_and_b32_e32 v235, s30, v223
	v_max_f32_e32 v232, s31, v232
	v_max_f32_e32 v233, s31, v233
	v_max_f32_e32 v234, s31, v234
	v_max_f32_e32 v235, s31, v235
	v_rcp_f32_e32 v232, v232
	v_rcp_f32_e32 v233, v233
	v_rcp_f32_e32 v234, v234
	v_rcp_f32_e32 v235, v235
	v_lshlrev_b32_e32 v224, 16, v220
	v_and_b32_e32 v225, s30, v220
	v_lshlrev_b32_e32 v242, 16, v221
	v_and_b32_e32 v243, s30, v221
	v_max_f32_e32 v224, s31, v224
	v_max_f32_e32 v225, s31, v225
	v_max_f32_e32 v242, s31, v242
	v_max_f32_e32 v243, s31, v243
	v_pk_mul_f32 v[232:233], v[232:233], v[224:225]
	v_pk_mul_f32 v[234:235], v[234:235], v[242:243]
	v_pk_mul_f32 v[0:1], v[0:1], v[232:233]
	v_pk_mul_f32 v[2:3], v[2:3], v[234:235]
	s_mov_b32 s76, s53
	s_mov_b32 s78, s88
	s_mov_b32 s48, s52
	s_mov_b32 s77, s87
	s_mov_b64 s[46:47], s[56:57]
	s_mov_b64 s[44:45], s[54:55]
	s_mov_b32 s51, s86
	s_branch .LBB0_294
.Lgm_fin:
	s_add_u32 s38, s24, 0x17b09000
	s_addc_u32 s39, s25, 0
	v_lshl_or_b32 v67, s78, 8, v174
	v_lshlrev_b32_e32 v67, 1, v67
	v_lshl_add_u32 v67, v66, 12, v67
	global_load_dwordx2 v[132:133], v64, s[34:35] offset:0
	global_load_dwordx2 v[134:135], v64, s[34:35] offset:32
	global_load_dwordx2 v[136:137], v64, s[34:35] offset:256
	global_load_dwordx2 v[138:139], v64, s[34:35] offset:288
	v_add_u32_e32 v64, 0x30000, v64
	global_load_dwordx2 v[140:141], v64, s[34:35] offset:0
	global_load_dwordx2 v[142:143], v64, s[34:35] offset:32
	global_load_dwordx2 v[144:145], v64, s[34:35] offset:256
	global_load_dwordx2 v[146:147], v64, s[34:35] offset:288
	v_add_u32_e32 v64, 0x30000, v64
	global_load_dwordx2 v[148:149], v64, s[34:35] offset:0
	global_load_dwordx2 v[150:151], v64, s[34:35] offset:32
	global_load_dwordx2 v[152:153], v64, s[34:35] offset:256
	global_load_dwordx2 v[154:155], v64, s[34:35] offset:288
	v_add_u32_e32 v64, 0x30000, v64
	global_load_dwordx2 v[156:157], v64, s[34:35] offset:0
	global_load_dwordx2 v[158:159], v64, s[34:35] offset:32
	global_load_dwordx2 v[160:161], v64, s[34:35] offset:256
	global_load_dwordx2 v[162:163], v64, s[34:35] offset:288
	v_add_u32_e32 v64, 0xf0000, v64
	global_load_dwordx2 v[164:165], v64, s[34:35] offset:0
	global_load_dwordx2 v[166:167], v64, s[34:35] offset:32
	global_load_dwordx2 v[196:197], v64, s[34:35] offset:256
	global_load_dwordx2 v[198:199], v64, s[34:35] offset:288
	v_add_u32_e32 v64, 0x30000, v64
	global_load_dwordx2 v[200:201], v64, s[34:35] offset:0
	global_load_dwordx2 v[202:203], v64, s[34:35] offset:32
	global_load_dwordx2 v[204:205], v64, s[34:35] offset:256
	global_load_dwordx2 v[206:207], v64, s[34:35] offset:288
	v_add_u32_e32 v64, 0x30000, v64
	global_load_dwordx2 v[208:209], v64, s[34:35] offset:0
	global_load_dwordx2 v[210:211], v64, s[34:35] offset:32
	global_load_dwordx2 v[212:213], v64, s[34:35] offset:256
	global_load_dwordx2 v[214:215], v64, s[34:35] offset:288
	v_add_u32_e32 v64, 0x30000, v64
	global_load_dwordx2 v[216:217], v64, s[34:35] offset:0
	global_load_dwordx2 v[218:219], v64, s[34:35] offset:32
	global_load_dwordx2 v[220:221], v64, s[34:35] offset:256
	global_load_dwordx2 v[222:223], v64, s[34:35] offset:288
	s_waitcnt vmcnt(31)
	v_lshlrev_b32_e32 v232, 16, v132
	v_and_b32_e32 v233, s30, v132
	v_lshlrev_b32_e32 v234, 16, v133
	v_and_b32_e32 v235, s30, v133
	v_max_f32_e32 v232, s31, v232
	v_max_f32_e32 v233, s31, v233
	v_max_f32_e32 v234, s31, v234
	v_max_f32_e32 v235, s31, v235
	v_pk_mul_f32 v[224:225], v[128:129], v[232:233]
	v_pk_mul_f32 v[242:243], v[130:131], v[234:235]
	v_cvt_pk_bf16_f32 v232, v224, v225
	v_cvt_pk_bf16_f32 v233, v242, v243
	global_store_dwordx2 v67, v[232:233], s[38:39] offset:0
	s_waitcnt vmcnt(31)
	v_lshlrev_b32_e32 v232, 16, v134
	v_and_b32_e32 v233, s30, v134
	v_lshlrev_b32_e32 v234, 16, v135
	v_and_b32_e32 v235, s30, v135
	v_max_f32_e32 v232, s31, v232
	v_max_f32_e32 v233, s31, v233
	v_max_f32_e32 v234, s31, v234
	v_max_f32_e32 v235, s31, v235
	v_pk_mul_f32 v[224:225], v[124:125], v[232:233]
	v_pk_mul_f32 v[242:243], v[126:127], v[234:235]
	v_cvt_pk_bf16_f32 v232, v224, v225
	v_cvt_pk_bf16_f32 v233, v242, v243
	global_store_dwordx2 v67, v[232:233], s[38:39] offset:32
	s_waitcnt vmcnt(31)
; __device__ __forceinline__ u32x2 pack4(f32x4 v) { u32x2 r; r[0] = cvt_pk(v[0], v[1]); r[1] = cvt_pk(v[2], v[3]); return r; }
; __device__ __forceinline__ f32x4 unpack4(u32x2 u) { f32x4 r; r[0] = bflo(u[0]); r[1] = bfhi(u[0]); r[2] = bflo(u[1]); r[3] = bfhi(u[1]); return r; }
; __device__ __forceinline__ void epilogue(const Params& p, const Unit& u, const f32x4 (&acc)[2][2][4][2], int wr, int wc, int fr, int fq) {
;     ...
;             for (int n = 0; n < 2; ++n) {
;               const size_t row = (size_t)(row0 + ai * 128 + (mp * 2 + mm) * 16);
;               const int col = cb + bj * 128 + n * 16;
;               f32x4 v = acc[ai][bj][mp * 2 + mm][n] * unpack4(gr[mm][bj][n]);
;               if (seg > 0) v += mv[mm][bj][n];
;               if (seg < 2) *(f32x4*)(mf + row * 2048 + col) = v;
;               else *(u32x2*)(mb + row * 2048 + col) = pack4(v);
;             }
	v_lshlrev_b32_e32 v232, 16, v136
	v_and_b32_e32 v233, s30, v136
	v_lshlrev_b32_e32 v234, 16, v137
	v_and_b32_e32 v235, s30, v137
	v_max_f32_e32 v232, s31, v232
	v_max_f32_e32 v233, s31, v233
	v_max_f32_e32 v234, s31, v234
	v_max_f32_e32 v235, s31, v235
	v_pk_mul_f32 v[224:225], v[96:97], v[232:233]
	v_pk_mul_f32 v[242:243], v[98:99], v[234:235]
	v_cvt_pk_bf16_f32 v232, v224, v225
	v_cvt_pk_bf16_f32 v233, v242, v243
	global_store_dwordx2 v67, v[232:233], s[38:39] offset:256
	s_waitcnt vmcnt(31)
	v_lshlrev_b32_e32 v232, 16, v138
	v_and_b32_e32 v233, s30, v138
	v_lshlrev_b32_e32 v234, 16, v139
	v_and_b32_e32 v235, s30, v139
	v_max_f32_e32 v232, s31, v232
	v_max_f32_e32 v233, s31, v233
	v_max_f32_e32 v234, s31, v234
	v_max_f32_e32 v235, s31, v235
	v_pk_mul_f32 v[224:225], v[92:93], v[232:233]
	v_pk_mul_f32 v[242:243], v[94:95], v[234:235]
	v_cvt_pk_bf16_f32 v232, v224, v225
	v_cvt_pk_bf16_f32 v233, v242, v243
	global_store_dwordx2 v67, v[232:233], s[38:39] offset:288
	v_add_u32_e32 v67, 0x10000, v67
	s_waitcnt vmcnt(31)
	v_lshlrev_b32_e32 v232, 16, v140
	v_and_b32_e32 v233, s30, v140
	v_lshlrev_b32_e32 v234, 16, v141
	v_and_b32_e32 v235, s30, v141
	v_max_f32_e32 v232, s31, v232
	v_max_f32_e32 v233, s31, v233
	v_max_f32_e32 v234, s31, v234
	v_max_f32_e32 v235, s31, v235
	v_pk_mul_f32 v[224:225], v[120:121], v[232:233]
	v_pk_mul_f32 v[242:243], v[122:123], v[234:235]
	v_cvt_pk_bf16_f32 v232, v224, v225
	v_cvt_pk_bf16_f32 v233, v242, v243
	global_store_dwordx2 v67, v[232:233], s[38:39] offset:0
	s_waitcnt vmcnt(31)
	v_lshlrev_b32_e32 v232, 16, v142
	v_and_b32_e32 v233, s30, v142
	v_lshlrev_b32_e32 v234, 16, v143
	v_and_b32_e32 v235, s30, v143
	v_max_f32_e32 v232, s31, v232
	v_max_f32_e32 v233, s31, v233
	v_max_f32_e32 v234, s31, v234
	v_max_f32_e32 v235, s31, v235
	v_pk_mul_f32 v[224:225], v[116:117], v[232:233]
	v_pk_mul_f32 v[242:243], v[118:119], v[234:235]
	v_cvt_pk_bf16_f32 v232, v224, v225
	v_cvt_pk_bf16_f32 v233, v242, v243
	global_store_dwordx2 v67, v[232:233], s[38:39] offset:32
	s_waitcnt vmcnt(31)
	v_lshlrev_b32_e32 v232, 16, v144
	v_and_b32_e32 v233, s30, v144
	v_lshlrev_b32_e32 v234, 16, v145
	v_and_b32_e32 v235, s30, v145
	v_max_f32_e32 v232, s31, v232
	v_max_f32_e32 v233, s31, v233
	v_max_f32_e32 v234, s31, v234
	v_max_f32_e32 v235, s31, v235
	v_pk_mul_f32 v[224:225], v[88:89], v[232:233]
	v_pk_mul_f32 v[242:243], v[90:91], v[234:235]
	v_cvt_pk_bf16_f32 v232, v224, v225
	v_cvt_pk_bf16_f32 v233, v242, v243
	global_store_dwordx2 v67, v[232:233], s[38:39] offset:256
	s_waitcnt vmcnt(31)
	v_lshlrev_b32_e32 v232, 16, v146
	v_and_b32_e32 v233, s30, v146
	v_lshlrev_b32_e32 v234, 16, v147
	v_and_b32_e32 v235, s30, v147
	v_max_f32_e32 v232, s31, v232
	v_max_f32_e32 v233, s31, v233
	v_max_f32_e32 v234, s31, v234
	v_max_f32_e32 v235, s31, v235
	v_pk_mul_f32 v[224:225], v[84:85], v[232:233]
	v_pk_mul_f32 v[242:243], v[86:87], v[234:235]
	v_cvt_pk_bf16_f32 v232, v224, v225
	v_cvt_pk_bf16_f32 v233, v242, v243
	global_store_dwordx2 v67, v[232:233], s[38:39] offset:288
	v_add_u32_e32 v67, 0x10000, v67
	s_waitcnt vmcnt(31)
	v_lshlrev_b32_e32 v232, 16, v148
	v_and_b32_e32 v233, s30, v148
	v_lshlrev_b32_e32 v234, 16, v149
	v_and_b32_e32 v235, s30, v149
	v_max_f32_e32 v232, s31, v232
	v_max_f32_e32 v233, s31, v233
	v_max_f32_e32 v234, s31, v234
	v_max_f32_e32 v235, s31, v235
	v_pk_mul_f32 v[224:225], v[112:113], v[232:233]
	v_pk_mul_f32 v[242:243], v[114:115], v[234:235]
	v_cvt_pk_bf16_f32 v232, v224, v225
	v_cvt_pk_bf16_f32 v233, v242, v243
	global_store_dwordx2 v67, v[232:233], s[38:39] offset:0
	s_waitcnt vmcnt(31)
	v_lshlrev_b32_e32 v232, 16, v150
	v_and_b32_e32 v233, s30, v150
	v_lshlrev_b32_e32 v234, 16, v151
	v_and_b32_e32 v235, s30, v151
	v_max_f32_e32 v232, s31, v232
	v_max_f32_e32 v233, s31, v233
	v_max_f32_e32 v234, s31, v234
	v_max_f32_e32 v235, s31, v235
	v_pk_mul_f32 v[224:225], v[108:109], v[232:233]
	v_pk_mul_f32 v[242:243], v[110:111], v[234:235]
	v_cvt_pk_bf16_f32 v232, v224, v225
	v_cvt_pk_bf16_f32 v233, v242, v243
	global_store_dwordx2 v67, v[232:233], s[38:39] offset:32
	s_waitcnt vmcnt(31)
	v_lshlrev_b32_e32 v232, 16, v152
	v_and_b32_e32 v233, s30, v152
	v_lshlrev_b32_e32 v234, 16, v153
	v_and_b32_e32 v235, s30, v153
	v_max_f32_e32 v232, s31, v232
	v_max_f32_e32 v233, s31, v233
	v_max_f32_e32 v234, s31, v234
	v_max_f32_e32 v235, s31, v235
	v_pk_mul_f32 v[224:225], v[80:81], v[232:233]
	v_pk_mul_f32 v[242:243], v[82:83], v[234:235]
	v_cvt_pk_bf16_f32 v232, v224, v225
	v_cvt_pk_bf16_f32 v233, v242, v243
	global_store_dwordx2 v67, v[232:233], s[38:39] offset:256
	s_waitcnt vmcnt(31)
	v_lshlrev_b32_e32 v232, 16, v154
	v_and_b32_e32 v233, s30, v154
	v_lshlrev_b32_e32 v234, 16, v155
	v_and_b32_e32 v235, s30, v155
	v_max_f32_e32 v232, s31, v232
	v_max_f32_e32 v233, s31, v233
	v_max_f32_e32 v234, s31, v234
	v_max_f32_e32 v235, s31, v235
	v_pk_mul_f32 v[224:225], v[76:77], v[232:233]
	v_pk_mul_f32 v[242:243], v[78:79], v[234:235]
	v_cvt_pk_bf16_f32 v232, v224, v225
	v_cvt_pk_bf16_f32 v233, v242, v243
	global_store_dwordx2 v67, v[232:233], s[38:39] offset:288
	v_add_u32_e32 v67, 0x10000, v67
	s_waitcnt vmcnt(31)
	v_lshlrev_b32_e32 v232, 16, v156
	v_and_b32_e32 v233, s30, v156
	v_lshlrev_b32_e32 v234, 16, v157
	v_and_b32_e32 v235, s30, v157
	v_max_f32_e32 v232, s31, v232
	v_max_f32_e32 v233, s31, v233
	v_max_f32_e32 v234, s31, v234
	v_max_f32_e32 v235, s31, v235
	v_pk_mul_f32 v[224:225], v[104:105], v[232:233]
	v_pk_mul_f32 v[242:243], v[106:107], v[234:235]
	v_cvt_pk_bf16_f32 v232, v224, v225
	v_cvt_pk_bf16_f32 v233, v242, v243
	global_store_dwordx2 v67, v[232:233], s[38:39] offset:0
	s_waitcnt vmcnt(31)
; __device__ __forceinline__ u32x2 pack4(f32x4 v) { u32x2 r; r[0] = cvt_pk(v[0], v[1]); r[1] = cvt_pk(v[2], v[3]); return r; }
; __device__ __forceinline__ f32x4 unpack4(u32x2 u) { f32x4 r; r[0] = bflo(u[0]); r[1] = bfhi(u[0]); r[2] = bflo(u[1]); r[3] = bfhi(u[1]); return r; }
; __device__ __forceinline__ void epilogue(const Params& p, const Unit& u, const f32x4 (&acc)[2][2][4][2], int wr, int wc, int fr, int fq) {
;     ...
;             for (int n = 0; n < 2; ++n) {
;               const size_t row = (size_t)(row0 + ai * 128 + (mp * 2 + mm) * 16);
;               const int col = cb + bj * 128 + n * 16;
;               f32x4 v = acc[ai][bj][mp * 2 + mm][n] * unpack4(gr[mm][bj][n]);
;               if (seg > 0) v += mv[mm][bj][n];
;               if (seg < 2) *(f32x4*)(mf + row * 2048 + col) = v;
;               else *(u32x2*)(mb + row * 2048 + col) = pack4(v);
;             }
	v_lshlrev_b32_e32 v232, 16, v158
	v_and_b32_e32 v233, s30, v158
	v_lshlrev_b32_e32 v234, 16, v159
	v_and_b32_e32 v235, s30, v159
	v_max_f32_e32 v232, s31, v232
	v_max_f32_e32 v233, s31, v233
	v_max_f32_e32 v234, s31, v234
	v_max_f32_e32 v235, s31, v235
	v_pk_mul_f32 v[224:225], v[100:101], v[232:233]
	v_pk_mul_f32 v[242:243], v[102:103], v[234:235]
	v_cvt_pk_bf16_f32 v232, v224, v225
	v_cvt_pk_bf16_f32 v233, v242, v243
	global_store_dwordx2 v67, v[232:233], s[38:39] offset:32
	s_waitcnt vmcnt(31)
	v_lshlrev_b32_e32 v232, 16, v160
	v_and_b32_e32 v233, s30, v160
	v_lshlrev_b32_e32 v234, 16, v161
	v_and_b32_e32 v235, s30, v161
	v_max_f32_e32 v232, s31, v232
	v_max_f32_e32 v233, s31, v233
	v_max_f32_e32 v234, s31, v234
	v_max_f32_e32 v235, s31, v235
	v_pk_mul_f32 v[224:225], v[72:73], v[232:233]
	v_pk_mul_f32 v[242:243], v[74:75], v[234:235]
	v_cvt_pk_bf16_f32 v232, v224, v225
	v_cvt_pk_bf16_f32 v233, v242, v243
	global_store_dwordx2 v67, v[232:233], s[38:39] offset:256
	s_waitcnt vmcnt(31)
	v_lshlrev_b32_e32 v232, 16, v162
	v_and_b32_e32 v233, s30, v162
	v_lshlrev_b32_e32 v234, 16, v163
	v_and_b32_e32 v235, s30, v163
	v_max_f32_e32 v232, s31, v232
	v_max_f32_e32 v233, s31, v233
	v_max_f32_e32 v234, s31, v234
	v_max_f32_e32 v235, s31, v235
	v_pk_mul_f32 v[224:225], v[68:69], v[232:233]
	v_pk_mul_f32 v[242:243], v[70:71], v[234:235]
	v_cvt_pk_bf16_f32 v232, v224, v225
	v_cvt_pk_bf16_f32 v233, v242, v243
	global_store_dwordx2 v67, v[232:233], s[38:39] offset:288
	v_add_u32_e32 v67, 0x50000, v67
	s_waitcnt vmcnt(31)
	v_lshlrev_b32_e32 v232, 16, v164
	v_and_b32_e32 v233, s30, v164
	v_lshlrev_b32_e32 v234, 16, v165
	v_and_b32_e32 v235, s30, v165
	v_max_f32_e32 v232, s31, v232
	v_max_f32_e32 v233, s31, v233
	v_max_f32_e32 v234, s31, v234
	v_max_f32_e32 v235, s31, v235
	v_pk_mul_f32 v[224:225], v[60:61], v[232:233]
	v_pk_mul_f32 v[242:243], v[62:63], v[234:235]
	v_cvt_pk_bf16_f32 v232, v224, v225
	v_cvt_pk_bf16_f32 v233, v242, v243
	global_store_dwordx2 v67, v[232:233], s[38:39] offset:0
	s_waitcnt vmcnt(31)
	v_lshlrev_b32_e32 v232, 16, v166
	v_and_b32_e32 v233, s30, v166
	v_lshlrev_b32_e32 v234, 16, v167
	v_and_b32_e32 v235, s30, v167
	v_max_f32_e32 v232, s31, v232
	v_max_f32_e32 v233, s31, v233
	v_max_f32_e32 v234, s31, v234
	v_max_f32_e32 v235, s31, v235
	v_pk_mul_f32 v[224:225], v[56:57], v[232:233]
	v_pk_mul_f32 v[242:243], v[58:59], v[234:235]
	v_cvt_pk_bf16_f32 v232, v224, v225
	v_cvt_pk_bf16_f32 v233, v242, v243
	global_store_dwordx2 v67, v[232:233], s[38:39] offset:32
	s_waitcnt vmcnt(31)
	v_lshlrev_b32_e32 v232, 16, v196
	v_and_b32_e32 v233, s30, v196
	v_lshlrev_b32_e32 v234, 16, v197
	v_and_b32_e32 v235, s30, v197
	v_max_f32_e32 v232, s31, v232
	v_max_f32_e32 v233, s31, v233
	v_max_f32_e32 v234, s31, v234
	v_max_f32_e32 v235, s31, v235
	v_pk_mul_f32 v[224:225], v[28:29], v[232:233]
	v_pk_mul_f32 v[242:243], v[30:31], v[234:235]
	v_cvt_pk_bf16_f32 v232, v224, v225
	v_cvt_pk_bf16_f32 v233, v242, v243
	global_store_dwordx2 v67, v[232:233], s[38:39] offset:256
	s_waitcnt vmcnt(31)
	v_lshlrev_b32_e32 v232, 16, v198
	v_and_b32_e32 v233, s30, v198
	v_lshlrev_b32_e32 v234, 16, v199
	v_and_b32_e32 v235, s30, v199
	v_max_f32_e32 v232, s31, v232
	v_max_f32_e32 v233, s31, v233
	v_max_f32_e32 v234, s31, v234
	v_max_f32_e32 v235, s31, v235
	v_pk_mul_f32 v[224:225], v[24:25], v[232:233]
	v_pk_mul_f32 v[242:243], v[26:27], v[234:235]
	v_cvt_pk_bf16_f32 v232, v224, v225
	v_cvt_pk_bf16_f32 v233, v242, v243
	global_store_dwordx2 v67, v[232:233], s[38:39] offset:288
	v_add_u32_e32 v67, 0x10000, v67
	s_waitcnt vmcnt(31)
	v_lshlrev_b32_e32 v232, 16, v200
	v_and_b32_e32 v233, s30, v200
	v_lshlrev_b32_e32 v234, 16, v201
	v_and_b32_e32 v235, s30, v201
	v_max_f32_e32 v232, s31, v232
	v_max_f32_e32 v233, s31, v233
	v_max_f32_e32 v234, s31, v234
	v_max_f32_e32 v235, s31, v235
	v_pk_mul_f32 v[224:225], v[52:53], v[232:233]
	v_pk_mul_f32 v[242:243], v[54:55], v[234:235]
	v_cvt_pk_bf16_f32 v232, v224, v225
	v_cvt_pk_bf16_f32 v233, v242, v243
	global_store_dwordx2 v67, v[232:233], s[38:39] offset:0
	s_waitcnt vmcnt(31)
	v_lshlrev_b32_e32 v232, 16, v202
	v_and_b32_e32 v233, s30, v202
	v_lshlrev_b32_e32 v234, 16, v203
	v_and_b32_e32 v235, s30, v203
	v_max_f32_e32 v232, s31, v232
	v_max_f32_e32 v233, s31, v233
	v_max_f32_e32 v234, s31, v234
	v_max_f32_e32 v235, s31, v235
	v_pk_mul_f32 v[224:225], v[48:49], v[232:233]
	v_pk_mul_f32 v[242:243], v[50:51], v[234:235]
	v_cvt_pk_bf16_f32 v232, v224, v225
	v_cvt_pk_bf16_f32 v233, v242, v243
	global_store_dwordx2 v67, v[232:233], s[38:39] offset:32
	s_waitcnt vmcnt(31)
; __device__ __forceinline__ u32x2 pack4(f32x4 v) { u32x2 r; r[0] = cvt_pk(v[0], v[1]); r[1] = cvt_pk(v[2], v[3]); return r; }
; __device__ __forceinline__ f32x4 unpack4(u32x2 u) { f32x4 r; r[0] = bflo(u[0]); r[1] = bfhi(u[0]); r[2] = bflo(u[1]); r[3] = bfhi(u[1]); return r; }
; __device__ __forceinline__ void epilogue(const Params& p, const Unit& u, const f32x4 (&acc)[2][2][4][2], int wr, int wc, int fr, int fq) {
;     ...
;             for (int n = 0; n < 2; ++n) {
;               const size_t row = (size_t)(row0 + ai * 128 + (mp * 2 + mm) * 16);
;               const int col = cb + bj * 128 + n * 16;
;               f32x4 v = acc[ai][bj][mp * 2 + mm][n] * unpack4(gr[mm][bj][n]);
;               if (seg > 0) v += mv[mm][bj][n];
;               if (seg < 2) *(f32x4*)(mf + row * 2048 + col) = v;
;               else *(u32x2*)(mb + row * 2048 + col) = pack4(v);
;             }
	v_lshlrev_b32_e32 v232, 16, v204
	v_and_b32_e32 v233, s30, v204
	v_lshlrev_b32_e32 v234, 16, v205
	v_and_b32_e32 v235, s30, v205
	v_max_f32_e32 v232, s31, v232
	v_max_f32_e32 v233, s31, v233
	v_max_f32_e32 v234, s31, v234
	v_max_f32_e32 v235, s31, v235
	v_pk_mul_f32 v[224:225], v[20:21], v[232:233]
	v_pk_mul_f32 v[242:243], v[22:23], v[234:235]
	v_cvt_pk_bf16_f32 v232, v224, v225
	v_cvt_pk_bf16_f32 v233, v242, v243
	global_store_dwordx2 v67, v[232:233], s[38:39] offset:256
	s_waitcnt vmcnt(31)
	v_lshlrev_b32_e32 v232, 16, v206
	v_and_b32_e32 v233, s30, v206
	v_lshlrev_b32_e32 v234, 16, v207
	v_and_b32_e32 v235, s30, v207
	v_max_f32_e32 v232, s31, v232
	v_max_f32_e32 v233, s31, v233
	v_max_f32_e32 v234, s31, v234
	v_max_f32_e32 v235, s31, v235
	v_pk_mul_f32 v[224:225], v[16:17], v[232:233]
	v_pk_mul_f32 v[242:243], v[18:19], v[234:235]
	v_cvt_pk_bf16_f32 v232, v224, v225
	v_cvt_pk_bf16_f32 v233, v242, v243
	global_store_dwordx2 v67, v[232:233], s[38:39] offset:288
	v_add_u32_e32 v67, 0x10000, v67
	s_waitcnt vmcnt(31)
	v_lshlrev_b32_e32 v232, 16, v208
	v_and_b32_e32 v233, s30, v208
	v_lshlrev_b32_e32 v234, 16, v209
	v_and_b32_e32 v235, s30, v209
	v_max_f32_e32 v232, s31, v232
	v_max_f32_e32 v233, s31, v233
	v_max_f32_e32 v234, s31, v234
	v_max_f32_e32 v235, s31, v235
	v_pk_mul_f32 v[224:225], v[44:45], v[232:233]
	v_pk_mul_f32 v[242:243], v[46:47], v[234:235]
	v_cvt_pk_bf16_f32 v232, v224, v225
	v_cvt_pk_bf16_f32 v233, v242, v243
	global_store_dwordx2 v67, v[232:233], s[38:39] offset:0
	s_waitcnt vmcnt(31)
	v_lshlrev_b32_e32 v232, 16, v210
	v_and_b32_e32 v233, s30, v210
	v_lshlrev_b32_e32 v234, 16, v211
	v_and_b32_e32 v235, s30, v211
	v_max_f32_e32 v232, s31, v232
	v_max_f32_e32 v233, s31, v233
	v_max_f32_e32 v234, s31, v234
	v_max_f32_e32 v235, s31, v235
	v_pk_mul_f32 v[224:225], v[40:41], v[232:233]
	v_pk_mul_f32 v[242:243], v[42:43], v[234:235]
	v_cvt_pk_bf16_f32 v232, v224, v225
	v_cvt_pk_bf16_f32 v233, v242, v243
	global_store_dwordx2 v67, v[232:233], s[38:39] offset:32
	s_waitcnt vmcnt(31)
	v_lshlrev_b32_e32 v232, 16, v212
	v_and_b32_e32 v233, s30, v212
	v_lshlrev_b32_e32 v234, 16, v213
	v_and_b32_e32 v235, s30, v213
	v_max_f32_e32 v232, s31, v232
	v_max_f32_e32 v233, s31, v233
	v_max_f32_e32 v234, s31, v234
	v_max_f32_e32 v235, s31, v235
	v_pk_mul_f32 v[224:225], v[12:13], v[232:233]
	v_pk_mul_f32 v[242:243], v[14:15], v[234:235]
	v_cvt_pk_bf16_f32 v232, v224, v225
	v_cvt_pk_bf16_f32 v233, v242, v243
	global_store_dwordx2 v67, v[232:233], s[38:39] offset:256
	s_waitcnt vmcnt(31)
	v_lshlrev_b32_e32 v232, 16, v214
	v_and_b32_e32 v233, s30, v214
	v_lshlrev_b32_e32 v234, 16, v215
	v_and_b32_e32 v235, s30, v215
	v_max_f32_e32 v232, s31, v232
	v_max_f32_e32 v233, s31, v233
	v_max_f32_e32 v234, s31, v234
	v_max_f32_e32 v235, s31, v235
	v_pk_mul_f32 v[224:225], v[8:9], v[232:233]
	v_pk_mul_f32 v[242:243], v[10:11], v[234:235]
	v_cvt_pk_bf16_f32 v232, v224, v225
	v_cvt_pk_bf16_f32 v233, v242, v243
	global_store_dwordx2 v67, v[232:233], s[38:39] offset:288
	v_add_u32_e32 v67, 0x10000, v67
	s_waitcnt vmcnt(31)
	v_lshlrev_b32_e32 v232, 16, v216
	v_and_b32_e32 v233, s30, v216
	v_lshlrev_b32_e32 v234, 16, v217
	v_and_b32_e32 v235, s30, v217
	v_max_f32_e32 v232, s31, v232
	v_max_f32_e32 v233, s31, v233
	v_max_f32_e32 v234, s31, v234
	v_max_f32_e32 v235, s31, v235
	v_pk_mul_f32 v[224:225], v[36:37], v[232:233]
	v_pk_mul_f32 v[242:243], v[38:39], v[234:235]
	v_cvt_pk_bf16_f32 v232, v224, v225
	v_cvt_pk_bf16_f32 v233, v242, v243
	global_store_dwordx2 v67, v[232:233], s[38:39] offset:0
	s_waitcnt vmcnt(31)
	v_lshlrev_b32_e32 v232, 16, v218
	v_and_b32_e32 v233, s30, v218
	v_lshlrev_b32_e32 v234, 16, v219
	v_and_b32_e32 v235, s30, v219
	v_max_f32_e32 v232, s31, v232
	v_max_f32_e32 v233, s31, v233
	v_max_f32_e32 v234, s31, v234
	v_max_f32_e32 v235, s31, v235
	v_pk_mul_f32 v[224:225], v[32:33], v[232:233]
	v_pk_mul_f32 v[242:243], v[34:35], v[234:235]
	v_cvt_pk_bf16_f32 v232, v224, v225
	v_cvt_pk_bf16_f32 v233, v242, v243
	global_store_dwordx2 v67, v[232:233], s[38:39] offset:32
	s_waitcnt vmcnt(31)
	v_lshlrev_b32_e32 v232, 16, v220
	v_and_b32_e32 v233, s30, v220
	v_lshlrev_b32_e32 v234, 16, v221
	v_and_b32_e32 v235, s30, v221
	v_max_f32_e32 v232, s31, v232
	v_max_f32_e32 v233, s31, v233
	v_max_f32_e32 v234, s31, v234
	v_max_f32_e32 v235, s31, v235
	v_pk_mul_f32 v[224:225], v[4:5], v[232:233]
	v_pk_mul_f32 v[242:243], v[6:7], v[234:235]
	v_cvt_pk_bf16_f32 v232, v224, v225
	v_cvt_pk_bf16_f32 v233, v242, v243
	global_store_dwordx2 v67, v[232:233], s[38:39] offset:256
	s_waitcnt vmcnt(31)
	v_lshlrev_b32_e32 v232, 16, v222
	v_and_b32_e32 v233, s30, v222
	v_lshlrev_b32_e32 v234, 16, v223
	v_and_b32_e32 v235, s30, v223
	v_max_f32_e32 v232, s31, v232
	v_max_f32_e32 v233, s31, v233
	v_max_f32_e32 v234, s31, v234
	v_max_f32_e32 v235, s31, v235
	v_pk_mul_f32 v[224:225], v[0:1], v[232:233]
	v_pk_mul_f32 v[242:243], v[2:3], v[234:235]
	v_cvt_pk_bf16_f32 v232, v224, v225
	v_cvt_pk_bf16_f32 v233, v242, v243
	global_store_dwordx2 v67, v[232:233], s[38:39] offset:288
	s_branch .LBB0_987
